# expert-table int8 quantization (input-only work): pu half moved from P7 to the start of P6 on the odd-slot workgroups, under the MFMA-bound K loops of the other half; P7 keeps the pv half
# speedup vs baseline: 1.0134x; 1.0134x over previous
; DI void phase7(const Params& P, char* smem) {
;     ...
;   for (int row = VB * 4 + wid; row < 2 * 16384; row += NVB * 4) {
;     const bool isv = row >= 16384; const int e = row & 16383;
;     const float* src = (isv ? P.pv : P.pu) + (long)e * 1024 + lane * 16;
;     float f[16];
; #pragma unroll
;     for (int k = 0; k < 4; ++k) { const float4 a = reinterpret_cast<const float4*>(src)[k]; f[4 * k] = a.x; f[4 * k + 1] = a.y; f[4 * k + 2] = a.z; f[4 * k + 3] = a.w; }
;     float am = 0.f;
; #pragma unroll
;     for (int k = 0; k < 16; ++k) am = fmaxf(am, fabsf(f[k]));
;     am = wave_max(am);
;     const float inv = am > 0.f ? 127.f / am : 0.f;
;     unsigned w[4];
; #pragma unroll
;     for (int k = 0; k < 4; ++k) {
;       unsigned pk = 0;
; #pragma unroll
;       for (int b = 0; b < 4; ++b) { int q = (int)rintf(f[4 * k + b] * inv); q = q > 127 ? 127 : (q < -127 ? -127 : q); pk |= ((unsigned)((isv ? q + 128 : q) & 0xff)) << (8 * b); }
;       w[k] = pk;
;     }
;     *reinterpret_cast<uint4*>(ws + (isv ? OFF_VQ + ((long)(lane >> 3) * 16384 + e) * 128 + (lane & 7) * 16 : OFF_UQ + (long)e * 1024 + lane * 16)) = make_uint4(w[0], w[1], w[2], w[3]);
;     if (lane == 0) reinterpret_cast<float*>(ws + (isv ? OFF_VS : OFF_US))[e] = am * (1.f / 127.f);
;   }
.LBB0_944:
	s_or_b64 exec, exec, s[0:1]
	s_add_u32 s38, s78, 0x8000000
	s_addc_u32 s39, s79, 0
	s_cmp_gt_i32 s75, 63
	s_waitcnt lgkmcnt(0)
	s_barrier
	s_cbranch_scc1 .LBB0_949
	s_bitcmp1_b32 s74, 3
	s_cbranch_scc0 .Lp6t_skip
	s_mov_b64 s[26:27], s[18:19]
	s_mov_b64 s[28:29], s[20:21]
	s_mov_b64 s[30:31], exec
	v_readlane_b32 s12, v254, 8
	v_lshlrev_b32_e32 v16, 4, v208
	v_cmp_eq_u32_e64 s[6:7], 0, v208
	v_and_b32_e32 v0, 12, v172
	v_lshl_add_u32 v0, s74, 3, v0
	v_or_b32_e32 v210, v0, v194
	s_lshl_b32 s12, s12, 3
	v_lshlrev_b32_e32 v0, 11, v189
	v_readlane_b32 s16, v254, 0
	v_mov_b32_e32 v19, 0
	v_and_b32_e32 v17, 0x1c000, v0
	v_and_b32_e32 v0, 0x70, v209
	v_readlane_b32 s17, v254, 1
	v_readlane_b32 s18, v254, 2
	v_readlane_b32 s19, v254, 3
	v_or_b32_e32 v24, 0x1000000, v0
	s_mov_b64 s[14:15], 0
	s_movk_i32 s2, 0x4000
	s_movk_i32 s4, 0x3fff
	v_mov_b32_e32 v25, s17
	v_mov_b32_e32 v26, s19
	v_mov_b32_e32 v27, s16
	v_mov_b32_e32 v28, s18
	v_lshlrev_b32_e32 v20, 2, v16
	v_mov_b32_e32 v21, v19
	s_mov_b32 s5, 0x42fe0000
	s_movk_i32 s13, 0xff81
	s_movk_i32 s16, 0xff
	s_movk_i32 s17, 0x3fff
	v_mov_b32_e32 v29, 0x7f
	v_mov_b32_e32 v30, v210
	v_readlane_b32 s20, v254, 4
	v_readlane_b32 s21, v254, 5
	v_readlane_b32 s22, v254, 6
	v_readlane_b32 s23, v254, 7
	v_mov_b32_e32 v148, v30
	v_and_b32_e32 v149, 0x3fff, v148
	v_cmp_lt_i32_e64 s[32:33], s4, v148
	v_lshlrev_b32_e32 v150, 12, v149
	v_mov_b32_e32 v151, 0
	s_nop 0
	v_cndmask_b32_e64 v153, v25, v26, s[32:33]
	v_cndmask_b32_e64 v152, v27, v28, s[32:33]
	v_lshl_add_u64 v[152:153], v[152:153], 0, v[150:151]
	v_lshl_add_u64 v[152:153], v[152:153], 0, v[20:21]
	global_load_dwordx4 v[132:135], v[152:153], off
	global_load_dwordx4 v[136:139], v[152:153], off offset:16
	global_load_dwordx4 v[140:143], v[152:153], off offset:32
	global_load_dwordx4 v[144:147], v[152:153], off offset:48
	s_waitcnt vmcnt(0)
	s_branch .Lp6t1_loop

; DI void phase7(const Params& P, char* smem) {
;     ...
;   for (int row = VB * 4 + wid; row < 2 * 16384; row += NVB * 4) {
;     const bool isv = row >= 16384; const int e = row & 16383;
;     const float* src = (isv ? P.pv : P.pu) + (long)e * 1024 + lane * 16;
;     float f[16];
; #pragma unroll
;     for (int k = 0; k < 4; ++k) { const float4 a = reinterpret_cast<const float4*>(src)[k]; f[4 * k] = a.x; f[4 * k + 1] = a.y; f[4 * k + 2] = a.z; f[4 * k + 3] = a.w; }
;     float am = 0.f;
; #pragma unroll
;     for (int k = 0; k < 16; ++k) am = fmaxf(am, fabsf(f[k]));
;     am = wave_max(am);
;     const float inv = am > 0.f ? 127.f / am : 0.f;
;     unsigned w[4];
; #pragma unroll
;     for (int k = 0; k < 4; ++k) {
;       unsigned pk = 0;
; #pragma unroll
;       for (int b = 0; b < 4; ++b) { int q = (int)rintf(f[4 * k + b] * inv); q = q > 127 ? 127 : (q < -127 ? -127 : q); pk |= ((unsigned)((isv ? q + 128 : q) & 0xff)) << (8 * b); }
;       w[k] = pk;
;     }
;     *reinterpret_cast<uint4*>(ws + (isv ? OFF_VQ + ((long)(lane >> 3) * 16384 + e) * 128 + (lane & 7) * 16 : OFF_UQ + (long)e * 1024 + lane * 16)) = make_uint4(w[0], w[1], w[2], w[3]);
;     if (lane == 0) reinterpret_cast<float*>(ws + (isv ? OFF_VS : OFF_US))[e] = am * (1.f / 127.f);
;   }
.Lp6t1_done:
	s_mov_b64 exec, s[30:31]
	s_waitcnt vmcnt(0)
	v_add_u32_e32 v210, 0xffffffc0, v210
	v_lshlrev_b32_e32 v0, 11, v189
	v_readlane_b32 s16, v254, 0
	v_mov_b32_e32 v19, 0
	v_and_b32_e32 v17, 0x1c000, v0
	v_and_b32_e32 v0, 0x70, v209
	v_readlane_b32 s17, v254, 1
	v_readlane_b32 s18, v254, 2
	v_readlane_b32 s19, v254, 3
	v_or_b32_e32 v24, 0x1000000, v0
	s_mov_b64 s[14:15], 0
	s_movk_i32 s2, 0x4000
	s_movk_i32 s4, 0x3fff
	v_mov_b32_e32 v25, s17
	v_mov_b32_e32 v26, s19
	v_mov_b32_e32 v27, s16
	v_mov_b32_e32 v28, s18
	v_lshlrev_b32_e32 v20, 2, v16
	v_mov_b32_e32 v21, v19
	s_mov_b32 s5, 0x42fe0000
	s_movk_i32 s13, 0xff81
	s_movk_i32 s16, 0xff
	s_movk_i32 s17, 0x3fff
	v_mov_b32_e32 v29, 0x7f
	v_mov_b32_e32 v30, v210
	v_readlane_b32 s20, v254, 4
	v_readlane_b32 s21, v254, 5
	v_readlane_b32 s22, v254, 6
	v_readlane_b32 s23, v254, 7
	v_mov_b32_e32 v148, v30
	v_and_b32_e32 v149, 0x3fff, v148
	v_cmp_lt_i32_e64 s[32:33], s4, v148
	v_lshlrev_b32_e32 v150, 12, v149
	v_mov_b32_e32 v151, 0
	s_nop 0
	v_cndmask_b32_e64 v153, v25, v26, s[32:33]
	v_cndmask_b32_e64 v152, v27, v28, s[32:33]
	v_lshl_add_u64 v[152:153], v[152:153], 0, v[150:151]
	v_lshl_add_u64 v[152:153], v[152:153], 0, v[20:21]
	global_load_dwordx4 v[132:135], v[152:153], off
	global_load_dwordx4 v[136:139], v[152:153], off offset:16
	global_load_dwordx4 v[140:143], v[152:153], off offset:32
	global_load_dwordx4 v[144:147], v[152:153], off offset:48
	s_waitcnt vmcnt(0)
	s_branch .Lp6t2_loop

; DI void phase7(const Params& P, char* smem) {
;     ...
;   for (int row = VB * 4 + wid; row < 2 * 16384; row += NVB * 4) {
;     const bool isv = row >= 16384; const int e = row & 16383;
;     const float* src = (isv ? P.pv : P.pu) + (long)e * 1024 + lane * 16;
;     float f[16];
; #pragma unroll
;     for (int k = 0; k < 4; ++k) { const float4 a = reinterpret_cast<const float4*>(src)[k]; f[4 * k] = a.x; f[4 * k + 1] = a.y; f[4 * k + 2] = a.z; f[4 * k + 3] = a.w; }
;     float am = 0.f;
; #pragma unroll
;     for (int k = 0; k < 16; ++k) am = fmaxf(am, fabsf(f[k]));
;     am = wave_max(am);
;     const float inv = am > 0.f ? 127.f / am : 0.f;
;     unsigned w[4];
; #pragma unroll
;     for (int k = 0; k < 4; ++k) {
;       unsigned pk = 0;
; #pragma unroll
;       for (int b = 0; b < 4; ++b) { int q = (int)rintf(f[4 * k + b] * inv); q = q > 127 ? 127 : (q < -127 ? -127 : q); pk |= ((unsigned)((isv ? q + 128 : q) & 0xff)) << (8 * b); }
;       w[k] = pk;
;     }
;     *reinterpret_cast<uint4*>(ws + (isv ? OFF_VQ + ((long)(lane >> 3) * 16384 + e) * 128 + (lane & 7) * 16 : OFF_UQ + (long)e * 1024 + lane * 16)) = make_uint4(w[0], w[1], w[2], w[3]);
;     if (lane == 0) reinterpret_cast<float*>(ws + (isv ? OFF_VS : OFF_US))[e] = am * (1.f / 127.f);
;   }
.Lp6t2_done:
	s_mov_b64 exec, s[30:31]
	s_waitcnt vmcnt(0)
	s_mov_b64 s[18:19], s[26:27]
	s_mov_b64 s[20:21], s[28:29]

; DI void phase7(const Params& P, char* smem) {
;     ...
;   for (int row = VB * 4 + wid; row < 2 * 16384; row += NVB * 4) {
;     const bool isv = row >= 16384; const int e = row & 16383;
;     const float* src = (isv ? P.pv : P.pu) + (long)e * 1024 + lane * 16;
;     float f[16];
; #pragma unroll
;     for (int k = 0; k < 4; ++k) { const float4 a = reinterpret_cast<const float4*>(src)[k]; f[4 * k] = a.x; f[4 * k + 1] = a.y; f[4 * k + 2] = a.z; f[4 * k + 3] = a.w; }
.LBB0_1006:
	s_or_b64 exec, exec, s[20:21]
	v_lshlrev_b32_e32 v0, 11, v189
	v_readlane_b32 s16, v254, 0
	v_mov_b32_e32 v19, 0
	v_and_b32_e32 v17, 0x1c000, v0
	v_and_b32_e32 v0, 0x70, v209
	v_readlane_b32 s17, v254, 1
	v_readlane_b32 s18, v254, 2
	v_readlane_b32 s19, v254, 3
	v_or_b32_e32 v24, 0x1000000, v0
	s_mov_b64 s[14:15], 0
	s_movk_i32 s2, 0x4000
	s_movk_i32 s4, 0x3fff
	v_mov_b32_e32 v25, s17
	v_mov_b32_e32 v26, s19
	v_mov_b32_e32 v27, s16
	v_mov_b32_e32 v28, s18
	v_lshlrev_b32_e32 v20, 2, v16
	v_mov_b32_e32 v21, v19
	s_mov_b32 s5, 0x42fe0000
	s_movk_i32 s13, 0xff81
	s_movk_i32 s16, 0xff
	s_movk_i32 s17, 0x7fff
	v_mov_b32_e32 v29, 0x7f
	v_add_u32_e32 v30, 0x4000, v210
	v_readlane_b32 s20, v254, 4
	v_readlane_b32 s21, v254, 5
	v_readlane_b32 s22, v254, 6
	v_readlane_b32 s23, v254, 7
	v_mov_b32_e32 v148, v30
	v_and_b32_e32 v149, 0x3fff, v148
	v_cmp_lt_i32_e64 s[32:33], s4, v148
	v_lshlrev_b32_e32 v150, 12, v149
	v_mov_b32_e32 v151, 0
	s_nop 0
	v_cndmask_b32_e64 v153, v25, v26, s[32:33]
	v_cndmask_b32_e64 v152, v27, v28, s[32:33]
	v_lshl_add_u64 v[152:153], v[152:153], 0, v[150:151]
	v_lshl_add_u64 v[152:153], v[152:153], 0, v[20:21]
	global_load_dwordx4 v[132:135], v[152:153], off
	global_load_dwordx4 v[136:139], v[152:153], off offset:16
	global_load_dwordx4 v[140:143], v[152:153], off offset:32
	global_load_dwordx4 v[144:147], v[152:153], off offset:48
	s_waitcnt vmcnt(0)
	s_branch .LBB0_1008
